# K/V projections as a distributed 64x64-tile mini-GEMM on all 256 workgroups (bf16 MFMA from L2), original 16 serial tiles skipped
# speedup vs baseline: 1.0014x; 1.0014x over previous
.LBB0_172:
	v_writelane_b32 v252, s54, 49
	s_nop 1
	v_writelane_b32 v252, s55, 50
	s_or_b64 exec, exec, s[0:1]
	v_writelane_b32 v252, s60, 51
	s_add_i32 s6, s30, s87
	s_add_u32 s0, s42, 0x200000
	v_writelane_b32 v252, s61, 52
	v_writelane_b32 v252, s0, 53
	s_addc_u32 s0, s43, 0
	v_writelane_b32 v252, s0, 54
	s_add_u32 s0, s42, 0x100000
	v_writelane_b32 v252, s0, 55
	s_addc_u32 s0, s43, 0
	s_abs_i32 s50, s30
	s_waitcnt lgkmcnt(0)
	v_cvt_f32_u32_e32 v0, s50
	v_writelane_b32 v252, s0, 56
	s_sub_i32 s0, 0, s50
	s_mov_b32 s7, s30
	v_rcp_iflag_f32_e32 v0, v0
	s_mov_b32 s11, 0
	v_mov_b32_e32 v129, 0
	s_ashr_i32 s33, s30, 31
	v_mul_f32_e32 v0, 0x4f7ffffe, v0
	v_cvt_u32_f32_e32 v0, v0
	s_mov_b64 s[12:13], 0x20000
	s_mov_b64 s[14:15], 0x40000
	s_mov_b64 s[16:17], 0x60000
	v_readfirstlane_b32 s1, v0
	s_mul_i32 s0, s0, s1
	s_mul_hi_u32 s0, s1, s0
	s_add_i32 s51, s1, s0
	s_add_i32 s0, 0, 0x20100
	s_mov_b64 s[18:19], 0x80
	s_mov_b64 s[20:21], 0x20080
	s_mov_b64 s[22:23], 0x40080
	s_mov_b64 s[24:25], 0x60080
	v_writelane_b32 v252, s0, 57
	v_mov_b32_e32 v143, 1.0
	v_mov_b32_e32 v144, 1
	s_mov_b32 s54, 0
	s_barrier
	v_readlane_b32 s0, v252, 34
	s_mov_b32 s99, 0
	s_cmp_lg_u32 s0, 0x100
	s_cbranch_scc1 .Lkv_done
	s_mov_b32 s99, 1
	v_readlane_b32 s0, v252, 0
	v_readlane_b32 s56, v252, 45
	v_readlane_b32 s57, v252, 46
	s_nop 0
	s_lshr_b32 s1, s0, 6
	s_and_b32 s4, s0, 63
	s_lshr_b32 s5, s1, 1
	s_and_b32 s10, s1, 1
	s_lshl_b32 s26, s5, 21
	s_add_u32 s28, s56, 0x300000
	s_addc_u32 s29, s57, 0
	s_add_u32 s28, s28, s26
	s_addc_u32 s29, s29, 0
	s_lshl_b32 s26, s5, 20
	s_add_u32 s30, s56, 0x4e00000
	s_addc_u32 s31, s57, 0
	s_add_u32 s30, s30, s26
	s_addc_u32 s31, s31, 0
	s_lshl_b32 s26, s5, 19
	s_cmp_eq_u32 s10, 0
	s_mov_b32 s27, 0x200000
	s_cselect_b32 s27, 0x100000, s27
	s_add_u32 s26, s26, s27
	s_add_u32 s36, s56, s26
	s_addc_u32 s37, s57, 0
	s_cmp_eq_u32 s10, 0
	s_cbranch_scc0 .Lkv_vtype
	s_mov_b64 s[44:45], s[28:29]
	s_mov_b64 s[46:47], s[30:31]
	s_movk_i32 s38, 0x200
	s_lshr_b32 s39, s4, 2
	s_and_b32 s48, s4, 3
	s_branch .Lkv_common
.Lkv_vtype:
	s_add_u32 s44, s30, 0x80000
	s_addc_u32 s45, s31, 0
	s_mov_b64 s[46:47], s[28:29]
	s_movk_i32 s38, 0x800
	s_lshr_b32 s39, s4, 4
	s_and_b32 s48, s4, 15
.Lkv_common:
	s_lshl_b32 s49, s39, 17
	s_add_u32 s44, s44, s49
	s_addc_u32 s45, s45, 0
	s_lshl_b32 s49, s48, 17
	s_add_u32 s46, s46, s49
	s_addc_u32 s47, s47, 0
	s_lshl_b32 s49, s38, 6
	s_mul_i32 s49, s49, s39
	s_lshl_b32 s55, s48, 7
	s_add_u32 s49, s49, s55
	s_add_u32 s36, s36, s49
	s_addc_u32 s37, s37, 0
	v_and_b32_e32 v0, 63, v241
	v_lshrrev_b32_e32 v1, 6, v241
	v_and_b32_e32 v20, 15, v0
	v_lshrrev_b32_e32 v21, 4, v0
	v_and_b32_e32 v22, 3, v1
	v_lshrrev_b32_e32 v23, 2, v1
	v_lshl_add_u32 v24, v22, 4, v20
	v_lshl_add_u32 v25, v23, 5, v20
	v_lshlrev_b32_e32 v26, 4, v21
	v_lshl_add_u32 v27, v24, 11, v26
	v_lshl_add_u32 v28, v25, 11, v26
	v_add_u32_e32 v29, 0x8000, v28
	v_mul_lo_u32 v30, v24, s38
	v_lshlrev_b32_e32 v31, 6, v23
	v_lshl_add_u32 v31, v21, 3, v31
	v_add_u32_e32 v30, v30, v31
	global_load_dwordx4 v[32:35], v27, s[44:45] offset:0
	global_load_dwordx4 v[36:39], v28, s[46:47] offset:0
	global_load_dwordx4 v[40:43], v29, s[46:47] offset:0
	global_load_dwordx4 v[44:47], v27, s[44:45] offset:64
	global_load_dwordx4 v[48:51], v28, s[46:47] offset:64
	global_load_dwordx4 v[52:55], v29, s[46:47] offset:64
	global_load_dwordx4 v[56:59], v27, s[44:45] offset:128
	global_load_dwordx4 v[60:63], v28, s[46:47] offset:128
	global_load_dwordx4 v[64:67], v29, s[46:47] offset:128
	global_load_dwordx4 v[68:71], v27, s[44:45] offset:192
	global_load_dwordx4 v[72:75], v28, s[46:47] offset:192
	global_load_dwordx4 v[76:79], v29, s[46:47] offset:192
	global_load_dwordx4 v[80:83], v27, s[44:45] offset:256
	global_load_dwordx4 v[84:87], v28, s[46:47] offset:256
	global_load_dwordx4 v[88:91], v29, s[46:47] offset:256
	global_load_dwordx4 v[92:95], v27, s[44:45] offset:320
	global_load_dwordx4 v[96:99], v28, s[46:47] offset:320
	global_load_dwordx4 v[100:103], v29, s[46:47] offset:320
	global_load_dwordx4 v[104:107], v27, s[44:45] offset:384
	global_load_dwordx4 v[108:111], v28, s[46:47] offset:384
	global_load_dwordx4 v[112:115], v29, s[46:47] offset:384
	global_load_dwordx4 v[116:119], v27, s[44:45] offset:448
	global_load_dwordx4 v[120:123], v28, s[46:47] offset:448
	global_load_dwordx4 v[124:127], v29, s[46:47] offset:448
	global_load_dwordx4 v[146:149], v27, s[44:45] offset:512
	global_load_dwordx4 v[150:153], v28, s[46:47] offset:512
	global_load_dwordx4 v[154:157], v29, s[46:47] offset:512
	global_load_dwordx4 v[158:161], v27, s[44:45] offset:576
	global_load_dwordx4 v[162:165], v28, s[46:47] offset:576
	global_load_dwordx4 v[166:169], v29, s[46:47] offset:576
	global_load_dwordx4 v[170:173], v27, s[44:45] offset:640
	global_load_dwordx4 v[174:177], v28, s[46:47] offset:640
	global_load_dwordx4 v[178:181], v29, s[46:47] offset:640
	global_load_dwordx4 v[182:185], v27, s[44:45] offset:704
	global_load_dwordx4 v[186:189], v28, s[46:47] offset:704
	global_load_dwordx4 v[190:193], v29, s[46:47] offset:704
	global_load_dwordx4 v[130:133], v27, s[44:45] offset:768
	global_load_dwordx4 v[134:137], v28, s[46:47] offset:768
	global_load_dwordx4 v[138:141], v29, s[46:47] offset:768
	global_load_dwordx4 v[194:197], v27, s[44:45] offset:832
	global_load_dwordx4 v[198:201], v28, s[46:47] offset:832
	global_load_dwordx4 v[202:205], v29, s[46:47] offset:832
	global_load_dwordx4 v[206:209], v27, s[44:45] offset:896
	global_load_dwordx4 v[210:213], v28, s[46:47] offset:896
	global_load_dwordx4 v[214:217], v29, s[46:47] offset:896
	global_load_dwordx4 v[218:221], v27, s[44:45] offset:960
	global_load_dwordx4 v[222:225], v28, s[46:47] offset:960
	global_load_dwordx4 v[226:229], v29, s[46:47] offset:960
	s_waitcnt vmcnt(36)
	v_mfma_f32_16x16x32_bf16 v[12:15], v[36:39], v[32:35], 0
	v_mfma_f32_16x16x32_bf16 v[16:19], v[40:43], v[32:35], 0
	v_mfma_f32_16x16x32_bf16 v[12:15], v[48:51], v[44:47], v[12:15]
	v_mfma_f32_16x16x32_bf16 v[16:19], v[52:55], v[44:47], v[16:19]
	v_mfma_f32_16x16x32_bf16 v[12:15], v[60:63], v[56:59], v[12:15]
	v_mfma_f32_16x16x32_bf16 v[16:19], v[64:67], v[56:59], v[16:19]
	v_mfma_f32_16x16x32_bf16 v[12:15], v[72:75], v[68:71], v[12:15]
	v_mfma_f32_16x16x32_bf16 v[16:19], v[76:79], v[68:71], v[16:19]
	global_load_dwordx4 v[32:35], v27, s[44:45] offset:1024
	global_load_dwordx4 v[36:39], v28, s[46:47] offset:1024
	global_load_dwordx4 v[40:43], v29, s[46:47] offset:1024
	global_load_dwordx4 v[44:47], v27, s[44:45] offset:1088
	global_load_dwordx4 v[48:51], v28, s[46:47] offset:1088
	global_load_dwordx4 v[52:55], v29, s[46:47] offset:1088
	global_load_dwordx4 v[56:59], v27, s[44:45] offset:1152
	global_load_dwordx4 v[60:63], v28, s[46:47] offset:1152
	global_load_dwordx4 v[64:67], v29, s[46:47] offset:1152
	global_load_dwordx4 v[68:71], v27, s[44:45] offset:1216
	global_load_dwordx4 v[72:75], v28, s[46:47] offset:1216
	global_load_dwordx4 v[76:79], v29, s[46:47] offset:1216
	s_waitcnt vmcnt(36)
	v_mfma_f32_16x16x32_bf16 v[12:15], v[84:87], v[80:83], v[12:15]
	v_mfma_f32_16x16x32_bf16 v[16:19], v[88:91], v[80:83], v[16:19]
	v_mfma_f32_16x16x32_bf16 v[12:15], v[96:99], v[92:95], v[12:15]
	v_mfma_f32_16x16x32_bf16 v[16:19], v[100:103], v[92:95], v[16:19]
	v_mfma_f32_16x16x32_bf16 v[12:15], v[108:111], v[104:107], v[12:15]
	v_mfma_f32_16x16x32_bf16 v[16:19], v[112:115], v[104:107], v[16:19]
	v_mfma_f32_16x16x32_bf16 v[12:15], v[120:123], v[116:119], v[12:15]
	v_mfma_f32_16x16x32_bf16 v[16:19], v[124:127], v[116:119], v[16:19]
	global_load_dwordx4 v[80:83], v27, s[44:45] offset:1280
	global_load_dwordx4 v[84:87], v28, s[46:47] offset:1280
	global_load_dwordx4 v[88:91], v29, s[46:47] offset:1280
	global_load_dwordx4 v[92:95], v27, s[44:45] offset:1344
	global_load_dwordx4 v[96:99], v28, s[46:47] offset:1344
	global_load_dwordx4 v[100:103], v29, s[46:47] offset:1344
	global_load_dwordx4 v[104:107], v27, s[44:45] offset:1408
	global_load_dwordx4 v[108:111], v28, s[46:47] offset:1408
	global_load_dwordx4 v[112:115], v29, s[46:47] offset:1408
	global_load_dwordx4 v[116:119], v27, s[44:45] offset:1472
	global_load_dwordx4 v[120:123], v28, s[46:47] offset:1472
	global_load_dwordx4 v[124:127], v29, s[46:47] offset:1472
	s_waitcnt vmcnt(36)
	v_mfma_f32_16x16x32_bf16 v[12:15], v[150:153], v[146:149], v[12:15]
	v_mfma_f32_16x16x32_bf16 v[16:19], v[154:157], v[146:149], v[16:19]
	v_mfma_f32_16x16x32_bf16 v[12:15], v[162:165], v[158:161], v[12:15]
	v_mfma_f32_16x16x32_bf16 v[16:19], v[166:169], v[158:161], v[16:19]
	v_mfma_f32_16x16x32_bf16 v[12:15], v[174:177], v[170:173], v[12:15]
	v_mfma_f32_16x16x32_bf16 v[16:19], v[178:181], v[170:173], v[16:19]
	v_mfma_f32_16x16x32_bf16 v[12:15], v[186:189], v[182:185], v[12:15]
	v_mfma_f32_16x16x32_bf16 v[16:19], v[190:193], v[182:185], v[16:19]
	global_load_dwordx4 v[146:149], v27, s[44:45] offset:1536
	global_load_dwordx4 v[150:153], v28, s[46:47] offset:1536
	global_load_dwordx4 v[154:157], v29, s[46:47] offset:1536
	global_load_dwordx4 v[158:161], v27, s[44:45] offset:1600
	global_load_dwordx4 v[162:165], v28, s[46:47] offset:1600
	global_load_dwordx4 v[166:169], v29, s[46:47] offset:1600
	global_load_dwordx4 v[170:173], v27, s[44:45] offset:1664
	global_load_dwordx4 v[174:177], v28, s[46:47] offset:1664
	global_load_dwordx4 v[178:181], v29, s[46:47] offset:1664
	global_load_dwordx4 v[182:185], v27, s[44:45] offset:1728
	global_load_dwordx4 v[186:189], v28, s[46:47] offset:1728
	global_load_dwordx4 v[190:193], v29, s[46:47] offset:1728
	s_waitcnt vmcnt(36)
	v_mfma_f32_16x16x32_bf16 v[12:15], v[134:137], v[130:133], v[12:15]
	v_mfma_f32_16x16x32_bf16 v[16:19], v[138:141], v[130:133], v[16:19]
	v_mfma_f32_16x16x32_bf16 v[12:15], v[198:201], v[194:197], v[12:15]
	v_mfma_f32_16x16x32_bf16 v[16:19], v[202:205], v[194:197], v[16:19]
	v_mfma_f32_16x16x32_bf16 v[12:15], v[210:213], v[206:209], v[12:15]
	v_mfma_f32_16x16x32_bf16 v[16:19], v[214:217], v[206:209], v[16:19]
	v_mfma_f32_16x16x32_bf16 v[12:15], v[222:225], v[218:221], v[12:15]
	v_mfma_f32_16x16x32_bf16 v[16:19], v[226:229], v[218:221], v[16:19]
	global_load_dwordx4 v[130:133], v27, s[44:45] offset:1792
	global_load_dwordx4 v[134:137], v28, s[46:47] offset:1792
	global_load_dwordx4 v[138:141], v29, s[46:47] offset:1792
	global_load_dwordx4 v[194:197], v27, s[44:45] offset:1856
	global_load_dwordx4 v[198:201], v28, s[46:47] offset:1856
	global_load_dwordx4 v[202:205], v29, s[46:47] offset:1856
	global_load_dwordx4 v[206:209], v27, s[44:45] offset:1920
	global_load_dwordx4 v[210:213], v28, s[46:47] offset:1920
	global_load_dwordx4 v[214:217], v29, s[46:47] offset:1920
	global_load_dwordx4 v[218:221], v27, s[44:45] offset:1984
	global_load_dwordx4 v[222:225], v28, s[46:47] offset:1984
	global_load_dwordx4 v[226:229], v29, s[46:47] offset:1984
	s_waitcnt vmcnt(36)
	v_mfma_f32_16x16x32_bf16 v[12:15], v[36:39], v[32:35], v[12:15]
	v_mfma_f32_16x16x32_bf16 v[16:19], v[40:43], v[32:35], v[16:19]
	v_mfma_f32_16x16x32_bf16 v[12:15], v[48:51], v[44:47], v[12:15]
	v_mfma_f32_16x16x32_bf16 v[16:19], v[52:55], v[44:47], v[16:19]
	v_mfma_f32_16x16x32_bf16 v[12:15], v[60:63], v[56:59], v[12:15]
	v_mfma_f32_16x16x32_bf16 v[16:19], v[64:67], v[56:59], v[16:19]
	v_mfma_f32_16x16x32_bf16 v[12:15], v[72:75], v[68:71], v[12:15]
	v_mfma_f32_16x16x32_bf16 v[16:19], v[76:79], v[68:71], v[16:19]
	s_waitcnt vmcnt(24)
	v_mfma_f32_16x16x32_bf16 v[12:15], v[84:87], v[80:83], v[12:15]
	v_mfma_f32_16x16x32_bf16 v[16:19], v[88:91], v[80:83], v[16:19]
	v_mfma_f32_16x16x32_bf16 v[12:15], v[96:99], v[92:95], v[12:15]
	v_mfma_f32_16x16x32_bf16 v[16:19], v[100:103], v[92:95], v[16:19]
	v_mfma_f32_16x16x32_bf16 v[12:15], v[108:111], v[104:107], v[12:15]
	v_mfma_f32_16x16x32_bf16 v[16:19], v[112:115], v[104:107], v[16:19]
	v_mfma_f32_16x16x32_bf16 v[12:15], v[120:123], v[116:119], v[12:15]
	v_mfma_f32_16x16x32_bf16 v[16:19], v[124:127], v[116:119], v[16:19]
	s_waitcnt vmcnt(12)
	v_mfma_f32_16x16x32_bf16 v[12:15], v[150:153], v[146:149], v[12:15]
	v_mfma_f32_16x16x32_bf16 v[16:19], v[154:157], v[146:149], v[16:19]
	v_mfma_f32_16x16x32_bf16 v[12:15], v[162:165], v[158:161], v[12:15]
	v_mfma_f32_16x16x32_bf16 v[16:19], v[166:169], v[158:161], v[16:19]
	v_mfma_f32_16x16x32_bf16 v[12:15], v[174:177], v[170:173], v[12:15]
	v_mfma_f32_16x16x32_bf16 v[16:19], v[178:181], v[170:173], v[16:19]
	v_mfma_f32_16x16x32_bf16 v[12:15], v[186:189], v[182:185], v[12:15]
	v_mfma_f32_16x16x32_bf16 v[16:19], v[190:193], v[182:185], v[16:19]
	s_waitcnt vmcnt(0)
	v_mfma_f32_16x16x32_bf16 v[12:15], v[134:137], v[130:133], v[12:15]
	v_mfma_f32_16x16x32_bf16 v[16:19], v[138:141], v[130:133], v[16:19]
	v_mfma_f32_16x16x32_bf16 v[12:15], v[198:201], v[194:197], v[12:15]
	v_mfma_f32_16x16x32_bf16 v[16:19], v[202:205], v[194:197], v[16:19]
	v_mfma_f32_16x16x32_bf16 v[12:15], v[210:213], v[206:209], v[12:15]
	v_mfma_f32_16x16x32_bf16 v[16:19], v[214:217], v[206:209], v[16:19]
	v_mfma_f32_16x16x32_bf16 v[12:15], v[222:225], v[218:221], v[12:15]
	v_mfma_f32_16x16x32_bf16 v[16:19], v[226:229], v[218:221], v[16:19]
	s_nop 7
	s_nop 3
	v_cvt_pk_bf16_f32 v20, v12, v13
	v_cvt_pk_bf16_f32 v21, v14, v15
	v_cvt_pk_bf16_f32 v22, v16, v17
	v_cvt_pk_bf16_f32 v23, v18, v19
	global_store_dwordx2 v30, v[20:21], s[36:37]
	global_store_dwordx2 v30, v[22:23], s[36:37] offset:32
.Lkv_done:
	s_branch .LBB0_175
.LBB0_173:
	s_waitcnt vmcnt(0)
	s_mov_b32 s76, s88
	s_mov_b64 s[64:65], s[90:91]
	s_barrier

.LBB0_175:
	s_and_b32 s10, s54, 1
	s_cmp_eq_u32 s10, 0
	s_cselect_b64 s[4:5], -1, 0
	s_and_b64 s[0:1], s[4:5], exec
	s_cselect_b32 s55, 4, 1
	s_lshl_b32 s0, s54, 2
	s_sub_i32 s0, s6, s0
	s_ashr_i32 s1, s0, 31
	s_abs_i32 s0, s0
	s_mul_hi_u32 s26, s0, s51
	s_mul_i32 s26, s26, s50
	s_sub_i32 s0, s0, s26
	s_sub_i32 s26, s0, s50
	s_cmp_ge_u32 s0, s50
	s_cselect_b32 s0, s26, s0
	s_sub_i32 s26, s0, s50
	s_cmp_ge_u32 s0, s50
	s_cselect_b32 s0, s26, s0
	s_xor_b32 s0, s0, s1
	s_sub_i32 s56, s0, s1
	s_lshl_b32 s0, s10, 1
	s_lshl_b32 s36, s55, s0
	v_mov_b32_e32 v4, v241
	s_cmp_ge_i32 s56, s36
	v_readfirstlane_b32 s30, v4
	s_cbranch_scc1 .LBB0_174
	s_cmp_eq_u32 s99, 1
	s_cbranch_scc1 .LBB0_174
	s_ashr_i32 s59, s56, 31
	s_lshr_b32 s0, s59, 29
	s_add_i32 s27, s56, s0
	s_lshr_b32 s57, s36, 3
	s_and_b32 s0, s27, -8
	s_and_b32 s58, s36, 5
	s_sub_i32 s10, s56, s0
	s_or_b32 s60, s57, 1
	s_cmp_ge_i32 s10, s58
	s_mov_b64 s[0:1], -1
	s_mul_i32 s61, s60, s58
	s_cbranch_scc0 .LBB0_178
	s_sub_i32 s0, s10, s58
	s_mul_i32 s0, s0, s57
	s_add_i32 s26, s0, s61
	s_mov_b64 s[0:1], 0

	.amdhsa_kernel _Z14fwd_megakernel4Args
		.amdhsa_group_segment_fixed_size 0
		.amdhsa_private_segment_fixed_size 0
		.amdhsa_kernarg_size 416
		.amdhsa_user_sgpr_count 2
		.amdhsa_user_sgpr_dispatch_ptr 0
		.amdhsa_user_sgpr_queue_ptr 0
		.amdhsa_user_sgpr_kernarg_segment_ptr 1
		.amdhsa_user_sgpr_dispatch_id 0
		.amdhsa_user_sgpr_kernarg_preload_length 0
		.amdhsa_user_sgpr_kernarg_preload_offset 0
		.amdhsa_user_sgpr_private_segment_size 0
		.amdhsa_uses_dynamic_stack 0
		.amdhsa_enable_private_segment 0
		.amdhsa_system_sgpr_workgroup_id_x 1
		.amdhsa_system_sgpr_workgroup_id_y 0
		.amdhsa_system_sgpr_workgroup_id_z 0
		.amdhsa_system_sgpr_workgroup_info 0
		.amdhsa_system_vgpr_workitem_id 2
		.amdhsa_next_free_vgpr 256
		.amdhsa_next_free_sgpr 100
		.amdhsa_accum_offset 256
		.amdhsa_reserve_vcc 1
		.amdhsa_float_round_mode_32 0
		.amdhsa_float_round_mode_16_64 0
		.amdhsa_float_denorm_mode_32 3
		.amdhsa_float_denorm_mode_16_64 3
		.amdhsa_dx10_clamp 1
		.amdhsa_ieee_mode 1
		.amdhsa_fp16_overflow 0
		.amdhsa_tg_split 0
		.amdhsa_exception_fp_ieee_invalid_op 0
		.amdhsa_exception_fp_denorm_src 0
		.amdhsa_exception_fp_ieee_div_zero 0
		.amdhsa_exception_fp_ieee_overflow 0
		.amdhsa_exception_fp_ieee_underflow 0
		.amdhsa_exception_fp_ieee_inexact 0
		.amdhsa_exception_int_div_zero 0
	.end_amdhsa_kernel

amdhsa.kernels:
  - .agpr_count:     0
    .args:
      - .offset:         0
        .size:           160
        .value_kind:     by_value
      - .offset:         160
        .size:           4
        .value_kind:     hidden_block_count_x
      - .offset:         164
        .size:           4
        .value_kind:     hidden_block_count_y
      - .offset:         168
        .size:           4
        .value_kind:     hidden_block_count_z
      - .offset:         172
        .size:           2
        .value_kind:     hidden_group_size_x
      - .offset:         174
        .size:           2
        .value_kind:     hidden_group_size_y
      - .offset:         176
        .size:           2
        .value_kind:     hidden_group_size_z
      - .offset:         178
        .size:           2
        .value_kind:     hidden_remainder_x
      - .offset:         180
        .size:           2
        .value_kind:     hidden_remainder_y
      - .offset:         182
        .size:           2
        .value_kind:     hidden_remainder_z
      - .offset:         200
        .size:           8
        .value_kind:     hidden_global_offset_x
      - .offset:         208
        .size:           8
        .value_kind:     hidden_global_offset_y
      - .offset:         216
        .size:           8
        .value_kind:     hidden_global_offset_z
      - .offset:         224
        .size:           2
        .value_kind:     hidden_grid_dims
      - .offset:         248
        .size:           8
        .value_kind:     hidden_multigrid_sync_arg
      - .offset:         280
        .size:           4
        .value_kind:     hidden_dynamic_lds_size
    .group_segment_fixed_size: 0
    .kernarg_segment_align: 8
    .kernarg_segment_size: 416
    .language:       OpenCL C
    .language_version:
      - 2
      - 0
    .max_flat_workgroup_size: 512
    .name:           _Z14fwd_megakernel4Args
    .private_segment_fixed_size: 0
    .sgpr_count:     106
    .sgpr_spill_count: 202
    .symbol:         _Z14fwd_megakernel4Args.kd
    .uniform_work_group_size: 1
    .uses_dynamic_stack: false
    .vgpr_count:     256
    .vgpr_spill_count: 0
    .wavefront_size: 64
